# selection-walk fast path: softmax row sum by a packed-add tree (8 instead of 16 adds)
# speedup vs baseline: 1.0155x; 1.0037x over previous
.LBB0_1265:
	v_cmp_lt_i32_e32 vcc, -1, v199
	s_nop 1
	v_max3_f32 v8, v126, s96, v127
	v_max3_f32 v8, v8, v128, v129
	v_max3_f32 v8, v8, v82, v83
	v_max3_f32 v8, v8, v84, v85
	v_max3_f32 v8, v8, v74, v75
	v_max3_f32 v8, v8, v76, v77
	v_max3_f32 v8, v8, v122, v123
	v_max3_f32 v8, v8, v124, v125
	v_cndmask_b32_e32 v8, v246, v8, vcc
	v_mov_b32_e32 v9, v8
	s_nop 1
	v_permlane16_swap_b32_e32 v8, v9
	v_max_f32_e32 v9, v8, v9
	v_mov_b32_e32 v8, v9
	s_nop 1
	v_permlane32_swap_b32_e32 v9, v8
	v_max3_f32 v10, v192, v9, v8
	v_max_f32_e32 v11, 0xe0ad78ec, v10
	v_mul_f32_e32 v11, s70, v11
	v_sub_f32_e32 v12, v192, v10
	v_cndmask_b32_e64 v11, -v246, v11, vcc
	v_mul_f32_e32 v12, 0x3e38aa3b, v12
	v_mul_f32_e32 v14, s70, v125
	v_exp_f32_e32 v12, v12
	v_sub_f32_e32 v14, v14, v11
	v_pk_fma_f32 v[126:127], v[126:127], s[70:71], v[10:11] op_sel:[0,0,1] op_sel_hi:[1,0,1] neg_lo:[0,0,1] neg_hi:[0,0,1]
	v_exp_f32_e32 v126, v126
	v_exp_f32_e32 v127, v127
	v_pk_fma_f32 v[128:129], v[128:129], s[70:71], v[10:11] op_sel:[0,0,1] op_sel_hi:[1,0,1] neg_lo:[0,0,1] neg_hi:[0,0,1]
	v_exp_f32_e32 v128, v128
	v_exp_f32_e32 v129, v129
	v_fma_f32 v0, v82, s70, -v11
	v_exp_f32_e32 v0, v0
	v_fma_f32 v1, v83, s70, -v11
	v_exp_f32_e32 v1, v1
	v_fma_f32 v2, v84, s70, -v11
	v_exp_f32_e32 v2, v2
	v_fma_f32 v3, v85, s70, -v11
	v_exp_f32_e32 v3, v3
	v_fma_f32 v4, v74, s70, -v11
	v_exp_f32_e32 v4, v4
	v_fma_f32 v5, v75, s70, -v11
	v_exp_f32_e32 v5, v5
	v_fma_f32 v6, v76, s70, -v11
	v_exp_f32_e32 v6, v6
	v_fma_f32 v7, v77, s70, -v11
	v_exp_f32_e32 v7, v7
	v_pk_fma_f32 v[122:123], v[122:123], s[70:71], v[10:11] op_sel:[0,0,1] op_sel_hi:[1,0,1] neg_lo:[0,0,1] neg_hi:[0,0,1]
	v_exp_f32_e32 v122, v122
	v_exp_f32_e32 v123, v123
	v_fma_f32 v124, v124, s70, -v11
	v_exp_f32_e32 v124, v124
	v_exp_f32_e32 v125, v14
	s_nop 0
	v_pk_add_f32 v[74:75], v[126:127], v[128:129]
	v_pk_add_f32 v[76:77], v[0:1], v[2:3]
	v_pk_add_f32 v[82:83], v[4:5], v[6:7]
	v_pk_add_f32 v[84:85], v[122:123], v[124:125]
	v_pk_add_f32 v[74:75], v[74:75], v[76:77]
	v_pk_add_f32 v[82:83], v[82:83], v[84:85]
	v_pk_add_f32 v[74:75], v[74:75], v[82:83]
	v_add_f32_e32 v13, v74, v75
	v_fma_f32 v133, v133, v12, v13
	v_pk_mul_f32 v[72:73], v[72:73], v[12:13] op_sel_hi:[1,0]
	v_pk_mul_f32 v[70:71], v[70:71], v[12:13] op_sel_hi:[1,0]
	v_pk_mul_f32 v[64:65], v[64:65], v[12:13] op_sel_hi:[1,0]
	v_pk_mul_f32 v[62:63], v[62:63], v[12:13] op_sel_hi:[1,0]
	v_pk_mul_f32 v[56:57], v[56:57], v[12:13] op_sel_hi:[1,0]
	v_pk_mul_f32 v[54:55], v[54:55], v[12:13] op_sel_hi:[1,0]
	v_pk_mul_f32 v[48:49], v[48:49], v[12:13] op_sel_hi:[1,0]
	v_pk_mul_f32 v[46:47], v[46:47], v[12:13] op_sel_hi:[1,0]
	v_mov_b32_e32 v192, v10
	v_cvt_pk_bf16_f32 v74, v126, v127
	v_cvt_pk_bf16_f32 v75, v128, v129
	v_cvt_pk_bf16_f32 v76, v0, v1
	v_cvt_pk_bf16_f32 v77, v2, v3
	v_cvt_pk_bf16_f32 v82, v4, v5
	v_cvt_pk_bf16_f32 v83, v6, v7
	v_cvt_pk_bf16_f32 v84, v122, v123
	v_cvt_pk_bf16_f32 v85, v124, v125
	s_branch .LBB0_1267

.LBB0_1270:
	v_cmp_lt_i32_e32 vcc, -1, v94
	s_nop 1
	v_max3_f32 v8, v98, s96, v99
	v_max3_f32 v8, v8, v100, v101
	v_max3_f32 v8, v8, v86, v87
	v_max3_f32 v8, v8, v88, v89
	v_max3_f32 v8, v8, v78, v79
	v_max3_f32 v8, v8, v80, v81
	v_max3_f32 v8, v8, v90, v91
	v_max3_f32 v8, v8, v92, v93
	v_cndmask_b32_e32 v8, v246, v8, vcc
	v_mov_b32_e32 v9, v8
	s_nop 1
	v_permlane16_swap_b32_e32 v8, v9
	v_max_f32_e32 v9, v8, v9
	v_mov_b32_e32 v8, v9
	s_nop 1
	v_permlane32_swap_b32_e32 v9, v8
	v_max3_f32 v10, v191, v9, v8
	v_max_f32_e32 v11, 0xe0ad78ec, v10
	v_mul_f32_e32 v11, s70, v11
	v_sub_f32_e32 v12, v191, v10
	v_cndmask_b32_e64 v11, -v246, v11, vcc
	v_mul_f32_e32 v12, 0x3e38aa3b, v12
	v_mul_f32_e32 v14, s70, v93
	v_exp_f32_e32 v12, v12
	v_sub_f32_e32 v14, v14, v11
	v_pk_fma_f32 v[98:99], v[98:99], s[70:71], v[10:11] op_sel:[0,0,1] op_sel_hi:[1,0,1] neg_lo:[0,0,1] neg_hi:[0,0,1]
	v_exp_f32_e32 v98, v98
	v_exp_f32_e32 v99, v99
	v_pk_fma_f32 v[100:101], v[100:101], s[70:71], v[10:11] op_sel:[0,0,1] op_sel_hi:[1,0,1] neg_lo:[0,0,1] neg_hi:[0,0,1]
	v_exp_f32_e32 v100, v100
	v_exp_f32_e32 v101, v101
	v_fma_f32 v0, v86, s70, -v11
	v_exp_f32_e32 v0, v0
	v_fma_f32 v1, v87, s70, -v11
	v_exp_f32_e32 v1, v1
	v_fma_f32 v2, v88, s70, -v11
	v_exp_f32_e32 v2, v2
	v_fma_f32 v3, v89, s70, -v11
	v_exp_f32_e32 v3, v3
	v_fma_f32 v4, v78, s70, -v11
	v_exp_f32_e32 v4, v4
	v_fma_f32 v5, v79, s70, -v11
	v_exp_f32_e32 v5, v5
	v_fma_f32 v6, v80, s70, -v11
	v_exp_f32_e32 v6, v6
	v_fma_f32 v7, v81, s70, -v11
	v_exp_f32_e32 v7, v7
	v_pk_fma_f32 v[90:91], v[90:91], s[70:71], v[10:11] op_sel:[0,0,1] op_sel_hi:[1,0,1] neg_lo:[0,0,1] neg_hi:[0,0,1]
	v_exp_f32_e32 v90, v90
	v_exp_f32_e32 v91, v91
	v_fma_f32 v92, v92, s70, -v11
	v_exp_f32_e32 v92, v92
	v_exp_f32_e32 v93, v14
	s_nop 0
	v_pk_add_f32 v[78:79], v[98:99], v[100:101]
	v_pk_add_f32 v[80:81], v[0:1], v[2:3]
	v_pk_add_f32 v[86:87], v[4:5], v[6:7]
	v_pk_add_f32 v[88:89], v[90:91], v[92:93]
	v_pk_add_f32 v[78:79], v[78:79], v[80:81]
	v_pk_add_f32 v[86:87], v[86:87], v[88:89]
	v_pk_add_f32 v[78:79], v[78:79], v[86:87]
	v_add_f32_e32 v13, v78, v79
	v_fma_f32 v152, v152, v12, v13
	v_pk_mul_f32 v[68:69], v[68:69], v[12:13] op_sel_hi:[1,0]
	v_pk_mul_f32 v[66:67], v[66:67], v[12:13] op_sel_hi:[1,0]
	v_pk_mul_f32 v[60:61], v[60:61], v[12:13] op_sel_hi:[1,0]
	v_pk_mul_f32 v[58:59], v[58:59], v[12:13] op_sel_hi:[1,0]
	v_pk_mul_f32 v[52:53], v[52:53], v[12:13] op_sel_hi:[1,0]
	v_pk_mul_f32 v[50:51], v[50:51], v[12:13] op_sel_hi:[1,0]
	v_pk_mul_f32 v[44:45], v[44:45], v[12:13] op_sel_hi:[1,0]
	v_pk_mul_f32 v[42:43], v[42:43], v[12:13] op_sel_hi:[1,0]
	v_mov_b32_e32 v191, v10
	v_cvt_pk_bf16_f32 v78, v98, v99
	v_cvt_pk_bf16_f32 v79, v100, v101
	v_cvt_pk_bf16_f32 v80, v0, v1
	v_cvt_pk_bf16_f32 v81, v2, v3
	v_cvt_pk_bf16_f32 v86, v4, v5
	v_cvt_pk_bf16_f32 v87, v6, v7
	v_cvt_pk_bf16_f32 v88, v90, v91
	v_cvt_pk_bf16_f32 v89, v92, v93
	s_branch .LBB0_1272
